# prep transposes: finish of tile A no longer waits for the prefetched tile B (separate counted waits on the next-tile-in-flight path)
# speedup vs baseline: 1.0018x; 1.0018x over previous
.LBB0_958:
	s_cbranch_execz .Ltr_b0
	s_waitcnt vmcnt(8)
	s_branch .Ltr_b1
.Ltr_b0:
	s_waitcnt vmcnt(0)
.Ltr_b1:
	s_or_b64 exec, exec, s[10:11]
	s_barrier
	ds_write2_b32 v85, v34, v35 offset1:1
	ds_write2_b32 v85, v36, v37 offset0:2 offset1:3
	ds_write2_b32 v79, v38, v39 offset1:1
	ds_write2_b32 v81, v40, v41 offset1:1
	ds_write2_b32 v91, v42, v43 offset1:1
	ds_write2_b32 v92, v44, v45 offset1:1
	ds_write2_b32 v93, v46, v47 offset1:1
	ds_write2_b32 v94, v48, v49 offset1:1
	ds_write2_b32 v95, v50, v51 offset1:1
	ds_write2_b32 v96, v52, v53 offset1:1
	ds_write2_b32 v97, v54, v55 offset1:1
	ds_write2_b32 v98, v56, v57 offset1:1
	ds_write2_b32 v99, v58, v59 offset1:1
	ds_write2_b32 v100, v60, v61 offset1:1
	ds_write2_b32 v101, v62, v63 offset1:1
	ds_write2_b32 v102, v64, v65 offset1:1
	s_waitcnt lgkmcnt(0)
	s_barrier
	ds_read2_b32 v[92:93], v88 offset1:130
	ds_read2_b32 v[94:95], v89 offset0:65 offset1:195
	v_add_u32_e32 v0, v80, v87
	v_ashrrev_i32_e32 v79, 31, v78
	v_mov_b32_e32 v71, v1
	s_waitcnt lgkmcnt(0)
	v_cvt_pk_bf16_f32 v92, v92, v94
	v_cvt_pk_bf16_f32 v93, v93, v95
	ds_read2_b32 v[94:95], v103 offset0:4 offset1:134
	ds_read2_b32 v[96:97], v104 offset0:69 offset1:199
	s_waitcnt lgkmcnt(0)
	v_cvt_pk_bf16_f32 v94, v94, v96
	v_cvt_pk_bf16_f32 v95, v95, v97
	ds_read2_b32 v[96:97], v105 offset0:8 offset1:138
	ds_read2_b32 v[98:99], v106 offset0:73 offset1:203
	s_waitcnt lgkmcnt(0)
	v_cvt_pk_bf16_f32 v96, v96, v98
	v_cvt_pk_bf16_f32 v97, v97, v99
	ds_read2_b32 v[98:99], v107 offset0:12 offset1:142
	ds_read2_b32 v[100:101], v108 offset0:77 offset1:207
	s_waitcnt lgkmcnt(0)
	v_cvt_pk_bf16_f32 v98, v98, v100
	v_cvt_pk_bf16_f32 v99, v99, v101
	ds_read2_b32 v[100:101], v109 offset0:16 offset1:146
	ds_read2_b32 v[102:103], v110 offset0:81 offset1:211
	s_waitcnt lgkmcnt(0)
	v_cvt_pk_bf16_f32 v100, v100, v102
	v_cvt_pk_bf16_f32 v101, v101, v103
	ds_read2_b32 v[102:103], v111 offset0:20 offset1:150
	ds_read2_b32 v[104:105], v112 offset0:85 offset1:215
	s_waitcnt lgkmcnt(0)
	v_cvt_pk_bf16_f32 v102, v102, v104
	v_cvt_pk_bf16_f32 v103, v103, v105
	ds_read2_b32 v[104:105], v113 offset0:24 offset1:154
	ds_read2_b32 v[106:107], v114 offset0:89 offset1:219
	s_waitcnt lgkmcnt(0)
	v_cvt_pk_bf16_f32 v104, v104, v106
	v_cvt_pk_bf16_f32 v105, v105, v107
	ds_read2_b32 v[106:107], v115 offset0:28 offset1:158
	ds_read2_b32 v[108:109], v116 offset0:93 offset1:223
	s_waitcnt lgkmcnt(0)
	v_cvt_pk_bf16_f32 v106, v106, v108
	v_cvt_pk_bf16_f32 v107, v107, v109
	v_mad_i64_i32 v[108:109], s[0:1], v90, v0, 0
	v_lshl_add_u64 v[108:109], v[108:109], 1, v[72:73]
	v_lshl_add_u64 v[108:109], v[78:79], 1, v[108:109]
	v_lshl_add_u64 v[108:109], v[108:109], 0, v[70:71]
	global_store_dwordx4 v[108:109], v[92:95], off
	global_store_dwordx4 v[108:109], v[96:99], off offset:16
	global_store_dwordx4 v[108:109], v[100:103], off offset:32
	global_store_dwordx4 v[108:109], v[104:107], off offset:48

.LBB0_986:
	s_cbranch_execz .Ltr_a0
	s_or_b64 exec, exec, s[10:11]
	v_add_u32_e32 v79, 0x1040, v85
	v_add_u32_e32 v81, 0x1048, v85
	v_add_u32_e32 v91, 0x2080, v85
	v_add_u32_e32 v92, 0x2088, v85
	v_add_u32_e32 v93, 0x30c0, v85
	v_add_u32_e32 v94, 0x30c8, v85
	v_add_u32_e32 v95, 0x4100, v85
	v_add_u32_e32 v96, 0x4108, v85
	v_add_u32_e32 v97, 0x5140, v85
	v_add_u32_e32 v98, 0x5148, v85
	v_add_u32_e32 v99, 0x6180, v85
	v_add_u32_e32 v100, 0x6188, v85
	v_add_u32_e32 v101, 0x71c0, v85
	v_add_u32_e32 v102, 0x71c8, v85
	s_waitcnt lgkmcnt(0)
	s_barrier
	s_waitcnt vmcnt(15)
	ds_write2_b32 v85, v2, v3 offset1:1
	ds_write2_b32 v85, v4, v5 offset0:2 offset1:3
	s_waitcnt vmcnt(14)
	ds_write2_b32 v79, v6, v7 offset1:1
	ds_write2_b32 v81, v8, v9 offset1:1
	s_waitcnt vmcnt(13)
	ds_write2_b32 v91, v10, v11 offset1:1
	ds_write2_b32 v92, v12, v13 offset1:1
	s_waitcnt vmcnt(12)
	ds_write2_b32 v93, v14, v15 offset1:1
	ds_write2_b32 v94, v16, v17 offset1:1
	s_waitcnt vmcnt(11)
	ds_write2_b32 v95, v18, v19 offset1:1
	ds_write2_b32 v96, v20, v21 offset1:1
	s_waitcnt vmcnt(10)
	ds_write2_b32 v97, v22, v23 offset1:1
	ds_write2_b32 v98, v24, v25 offset1:1
	s_waitcnt vmcnt(9)
	ds_write2_b32 v99, v26, v27 offset1:1
	ds_write2_b32 v100, v28, v29 offset1:1
	s_waitcnt vmcnt(8)
	ds_write2_b32 v101, v30, v31 offset1:1
	ds_write2_b32 v102, v32, v33 offset1:1
	s_branch .Ltr_a1

.Ltr_a1:
	s_waitcnt lgkmcnt(0)
	s_barrier
	ds_read2_b32 v[104:105], v88 offset1:130
	ds_read2_b32 v[106:107], v89 offset0:65 offset1:195
	v_add_u32_e32 v103, 0x400, v88
	v_add_u32_e32 v0, v76, v87
	v_ashrrev_i32_e32 v75, 31, v74
	v_mov_b32_e32 v71, v1
	s_waitcnt lgkmcnt(0)
	v_cvt_pk_bf16_f32 v118, v104, v106
	v_add_u32_e32 v104, 0x400, v89
	v_cvt_pk_bf16_f32 v119, v105, v107
	ds_read2_b32 v[106:107], v103 offset0:4 offset1:134
	ds_read2_b32 v[108:109], v104 offset0:69 offset1:199
	v_add_u32_e32 v105, 0x800, v88
	s_waitcnt lgkmcnt(0)
	v_cvt_pk_bf16_f32 v120, v106, v108
	v_add_u32_e32 v106, 0x800, v89
	v_cvt_pk_bf16_f32 v121, v107, v109
	ds_read2_b32 v[108:109], v105 offset0:8 offset1:138
	ds_read2_b32 v[110:111], v106 offset0:73 offset1:203
	v_add_u32_e32 v107, 0xc00, v88
	s_waitcnt lgkmcnt(0)
	v_cvt_pk_bf16_f32 v122, v108, v110
	v_add_u32_e32 v108, 0xc00, v89
	v_cvt_pk_bf16_f32 v123, v109, v111
	ds_read2_b32 v[110:111], v107 offset0:12 offset1:142
	ds_read2_b32 v[112:113], v108 offset0:77 offset1:207
	v_add_u32_e32 v109, 0x1000, v88
	s_waitcnt lgkmcnt(0)
	v_cvt_pk_bf16_f32 v124, v110, v112
	v_add_u32_e32 v110, 0x1000, v89
	v_cvt_pk_bf16_f32 v125, v111, v113
	ds_read2_b32 v[112:113], v109 offset0:16 offset1:146
	ds_read2_b32 v[114:115], v110 offset0:81 offset1:211
	v_add_u32_e32 v111, 0x1400, v88
	s_waitcnt lgkmcnt(0)
	v_cvt_pk_bf16_f32 v126, v112, v114
	v_add_u32_e32 v112, 0x1400, v89
	v_cvt_pk_bf16_f32 v127, v113, v115
	ds_read2_b32 v[114:115], v111 offset0:20 offset1:150
	ds_read2_b32 v[116:117], v112 offset0:85 offset1:215
	v_add_u32_e32 v113, 0x1800, v88
	s_waitcnt lgkmcnt(0)
	v_cvt_pk_bf16_f32 v128, v114, v116
	v_add_u32_e32 v114, 0x1800, v89
	v_cvt_pk_bf16_f32 v129, v115, v117
	ds_read2_b32 v[116:117], v113 offset0:24 offset1:154
	ds_read2_b32 v[130:131], v114 offset0:89 offset1:219
	v_add_u32_e32 v115, 0x1c00, v88
	ds_read2_b32 v[132:133], v115 offset0:28 offset1:158
	s_waitcnt lgkmcnt(1)
	v_cvt_pk_bf16_f32 v130, v116, v130
	v_add_u32_e32 v116, 0x1c00, v89
	ds_read2_b32 v[134:135], v116 offset0:93 offset1:223
	v_cvt_pk_bf16_f32 v131, v117, v131
	s_waitcnt lgkmcnt(0)
	v_cvt_pk_bf16_f32 v132, v132, v134
	v_cvt_pk_bf16_f32 v133, v133, v135
	v_mad_i64_i32 v[134:135], s[0:1], v0, v83, 0
	v_lshl_add_u64 v[134:135], v[134:135], 1, v[66:67]
	v_lshl_add_u64 v[134:135], v[74:75], 1, v[134:135]
	v_readlane_b32 s0, v254, 28
	v_lshl_add_u64 v[134:135], v[134:135], 0, v[70:71]
	global_store_dwordx4 v[134:135], v[118:121], off
	global_store_dwordx4 v[134:135], v[122:125], off offset:16
	global_store_dwordx4 v[134:135], v[126:129], off offset:32
	global_store_dwordx4 v[134:135], v[130:133], off offset:48
	v_add_u32_e32 v75, s0, v77
	s_and_saveexec_b64 s[4:5], vcc
	s_cbranch_execz .LBB0_959
	s_movk_i32 s0, 0x2c08
	v_cmp_gt_i32_e32 vcc, s0, v75
	s_and_saveexec_b64 s[10:11], vcc
	s_cbranch_execz .LBB0_958
	s_mov_b32 s0, 0x5d065bf
	v_mul_hi_i32 v0, v75, s0
	v_lshrrev_b32_e32 v2, 31, v0
	v_ashrrev_i32_e32 v0, 7, v0
	v_add_u32_e32 v2, v0, v2
	s_movk_i32 s0, 0xe9fc
	v_mul_i32_i24_e32 v3, 0xffffe9fc, v2
	v_mad_i32_i24 v0, v2, s0, v75
	v_readlane_b32 s0, v254, 28
	s_nop 1
	v_add3_u32 v6, s0, v3, v77
	s_movk_i32 s0, 0x34f
	v_cmp_lt_i32_e32 vcc, s0, v6
	s_and_saveexec_b64 s[0:1], vcc
	s_xor_b64 s[12:13], exec, s[0:1]
	s_cbranch_execz .LBB0_1010
	s_movk_i32 s0, 0x373
	v_cmp_lt_u32_e32 vcc, s0, v6
	s_and_saveexec_b64 s[0:1], vcc
	s_xor_b64 s[14:15], exec, s[0:1]
	s_cbranch_execz .LBB0_1007
	s_movk_i32 s0, 0x383
	v_ashrrev_i32_e32 v3, 31, v2
	v_cmp_lt_u32_e32 vcc, s0, v6
	s_and_saveexec_b64 s[0:1], vcc
	s_xor_b64 s[16:17], exec, s[0:1]
	s_cbranch_execz .LBB0_1004
	s_movk_i32 s0, 0x583
	v_cmp_lt_u32_e32 vcc, s0, v6
	s_and_saveexec_b64 s[0:1], vcc
	s_xor_b64 s[70:71], exec, s[0:1]
	s_cbranch_execz .LBB0_1001
	s_movk_i32 s0, 0xb03
	v_cmp_lt_u32_e32 vcc, s0, v6
	s_mov_b32 s0, 0x2c00000
	v_mad_i64_i32 v[4:5], s[0:1], v2, s0, 0
	s_and_saveexec_b64 s[0:1], vcc
	s_xor_b64 s[0:1], exec, s[0:1]
	s_cbranch_execz .LBB0_998
	s_movk_i32 s36, 0x1083
	v_cmp_lt_u32_e32 vcc, s36, v6
	s_mov_b32 s36, 0x1600000
	v_mad_i64_i32 v[2:3], s[52:53], v2, s36, 0
	s_and_saveexec_b64 s[52:53], vcc
	s_xor_b64 s[72:73], exec, s[52:53]
	s_cbranch_execz .LBB0_995
	v_readlane_b32 s36, v252, 49
	v_readlane_b32 s37, v252, 50
	v_readlane_b32 s38, v252, 51
	v_readlane_b32 s39, v252, 52
	v_readlane_b32 s40, v252, 53
	v_readlane_b32 s41, v252, 54
	v_readlane_b32 s42, v252, 55
	v_readlane_b32 s43, v252, 56
	v_readlane_b32 s44, v252, 57
	v_readlane_b32 s45, v252, 58
	v_readlane_b32 s46, v252, 59
	v_readlane_b32 s47, v252, 60
	v_readlane_b32 s48, v252, 61
	v_readlane_b32 s49, v252, 62
	v_readlane_b32 s50, v252, 63
	v_readlane_b32 s51, v253, 0
	v_add_u32_e32 v0, 0xffffef7c, v6
	s_nop 0
	v_lshl_add_u64 v[26:27], s[50:51], 0, v[4:5]
	v_readlane_b32 s36, v253, 1
	v_readlane_b32 s50, v253, 15
	v_readlane_b32 s51, v253, 16
	v_readlane_b32 s37, v253, 2
	v_readlane_b32 s38, v253, 3
	v_readlane_b32 s39, v253, 4
	v_readlane_b32 s40, v253, 5
	v_readlane_b32 s41, v253, 6
	v_readlane_b32 s42, v253, 7
	v_readlane_b32 s43, v253, 8
	v_readlane_b32 s44, v253, 9
	v_readlane_b32 s45, v253, 10
	v_readlane_b32 s46, v253, 11
	v_readlane_b32 s47, v253, 12
	v_readlane_b32 s48, v253, 13
	v_readlane_b32 s49, v253, 14
	v_lshl_add_u64 v[66:67], s[50:51], 0, v[2:3]
